# group-local (4 workgroups, one XCC) synchronisation at the P4->P5 and P6->P7 seams when the run-time placement census allows it; P5->P6 grid barrier keeps its L2 write-back
# speedup vs baseline: 1.0090x; 1.0069x over previous
; __device__ __forceinline__ unsigned xb_ld(unsigned* p)              { return __hip_atomic_load(p, __ATOMIC_RELAXED, __HIP_MEMORY_SCOPE_AGENT); }
; __device__ __forceinline__ unsigned xb_add(unsigned* p, unsigned v) { return __hip_atomic_fetch_add(p, v, __ATOMIC_RELAXED, __HIP_MEMORY_SCOPE_AGENT); }
; #define XB_SPIN(cond, bar) do { unsigned _sp = 0; while (cond) { __builtin_amdgcn_s_sleep(1); \
;     if ((++_sp & 255u) == 0u) { if (xb_ld(&(bar)[XB_TMO])) break; if (_sp > XB_SPIN_CAP) { atomicAdd(&(bar)[XB_TMO], 1u); break; } } } } while (0)
; #define SEAM(k) do { if (IN(k) && IN((k) + 1)) GRID_SYNC(); } while (0)
; __device__ __forceinline__ void xcd_barrier(const XcdBarrier& b) {
;     asm volatile("s_waitcnt vmcnt(0)" ::: "memory");
;     __syncthreads();
;     if (threadIdx.x == 0) {
;         unsigned* bar = b.bar;
;         __builtin_amdgcn_s_waitcnt(0);
;         unsigned nloc = b.st[0], nx = b.st[1];
;         if (nloc == 0u) { xcd_barrier_complete(bar, b.x, nloc, nx); b.st[0] = nloc; b.st[1] = nx; }
;         const unsigned old = xb_add(&bar[XB_XSUB(b.x)], 1u);
;         const unsigned gen = old / nloc;
;         if (old + 1u == (gen + 1u) * nloc) {
;             __builtin_amdgcn_fence(__ATOMIC_RELEASE, "agent");
;             asm volatile("s_waitcnt vmcnt(0)" ::: "memory");
;             const unsigned og = xb_add(&bar[XB_TOP], 1u);
;             const unsigned tg = og / nx;
;             if (og + 1u == (tg + 1u) * nx) xb_add(&bar[XB_TOPGEN], 1u);
;             else XB_SPIN(xb_ld(&bar[XB_TOPGEN]) == tg, bar);
;             __builtin_amdgcn_fence(__ATOMIC_ACQUIRE, "agent");
;             xb_add(&bar[XB_XGEN(b.x)], 1u);
;             asm volatile("s_waitcnt vmcnt(0)" ::: "memory");
;         } else {
;             XB_SPIN(xb_ld(&bar[XB_XGEN(b.x)]) == gen, bar);
;             __builtin_amdgcn_fence(__ATOMIC_ACQUIRE, "agent");
;             asm volatile("s_waitcnt vmcnt(0)" ::: "memory");
;         }
;     }
;     __syncthreads();
; }
; __global__ void __launch_bounds__(NTHR, 2) mk_fwd(MkArgs a) {
;     ...
;     SEAM(4);
.LBB9_591:
	s_cmp_gt_i32 s93, 5
	s_cselect_b64 s[0:1], -1, 0
	s_and_b64 s[2:3], s[6:7], s[0:1]
	s_andn2_b64 vcc, exec, s[2:3]
	s_cbranch_vccnz .LBB9_645
	s_waitcnt vmcnt(0)
	s_waitcnt vmcnt(0) lgkmcnt(0)
	s_barrier
	s_and_saveexec_b64 s[4:5], s[80:81]
	s_cbranch_execz .LBB9_644
	v_mov_b32_e32 v0, 0x24008
	ds_read_b32 v0, v0
	s_waitcnt lgkmcnt(0)
	v_readfirstlane_b32 s98, v0
	s_nop 3
	s_cmp_eq_u32 s98, 1
	s_cbranch_scc0 .Lgb4_orig
	s_and_b32 s98, s97, 63
	s_lshl_b32 s98, s98, 2
	s_add_i32 s98, s98, 0x3d00
	v_mov_b32_e32 v0, s98
	v_mov_b32_e32 v1, 1
	global_atomic_add v0, v1, s[90:91]
.Lgb4_poll:
	s_sleep 1
	global_load_dword v2, v0, s[90:91] sc1
	s_waitcnt vmcnt(0)
	v_cmp_gt_u32_e32 vcc, 4, v2
	s_cbranch_vccnz .Lgb4_poll
	buffer_inv sc1
	s_branch .LBB9_644
.Lgb4_orig:
	s_add_i32 s2, 0, 0x24000
	v_mov_b32_e32 v0, s2
	s_waitcnt vmcnt(0) expcnt(0) lgkmcnt(0)
	ds_read_b32 v2, v0
	s_add_i32 s2, 0, 0x24004
	v_mov_b32_e32 v0, s2
	ds_read_b32 v0, v0
	s_waitcnt lgkmcnt(1)
	v_cmp_ne_u32_e32 vcc, 0, v2
	s_cbranch_vccnz .LBB9_608
	s_add_u32 s6, s90, 0x1000
	s_addc_u32 s7, s91, 0
	s_add_u32 s8, s90, 0x1100
	s_addc_u32 s9, s91, 0
	s_add_u32 s10, s90, 0x1200
	s_addc_u32 s11, s91, 0
	s_mul_i32 s18, s95, s83
	s_add_u32 s12, s90, 0x1300
	s_mul_i32 s18, s18, s94
	s_addc_u32 s13, s91, 0
	s_mov_b32 s19, 1
	v_mov_b32_e32 v16, 0
	s_branch .LBB9_596

; __device__ __forceinline__ unsigned xb_ld(unsigned* p)              { return __hip_atomic_load(p, __ATOMIC_RELAXED, __HIP_MEMORY_SCOPE_AGENT); }
; __device__ __forceinline__ unsigned xb_add(unsigned* p, unsigned v) { return __hip_atomic_fetch_add(p, v, __ATOMIC_RELAXED, __HIP_MEMORY_SCOPE_AGENT); }
; #define XB_SPIN(cond, bar) do { unsigned _sp = 0; while (cond) { __builtin_amdgcn_s_sleep(1); \
;     if ((++_sp & 255u) == 0u) { if (xb_ld(&(bar)[XB_TMO])) break; if (_sp > XB_SPIN_CAP) { atomicAdd(&(bar)[XB_TMO], 1u); break; } } } } while (0)
; __device__ __forceinline__ void xcd_barrier(const XcdBarrier& b) {
;     ...
;         const unsigned old = xb_add(&bar[XB_XSUB(b.x)], 1u);
;         const unsigned gen = old / nloc;
;         if (old + 1u == (gen + 1u) * nloc) {
;             __builtin_amdgcn_fence(__ATOMIC_RELEASE, "agent");
;             asm volatile("s_waitcnt vmcnt(0)" ::: "memory");
;             const unsigned og = xb_add(&bar[XB_TOP], 1u);
;             const unsigned tg = og / nx;
;             if (og + 1u == (tg + 1u) * nx) xb_add(&bar[XB_TOPGEN], 1u);
;             else XB_SPIN(xb_ld(&bar[XB_TOPGEN]) == tg, bar);
;             __builtin_amdgcn_fence(__ATOMIC_ACQUIRE, "agent");
;             xb_add(&bar[XB_XGEN(b.x)], 1u);
;             asm volatile("s_waitcnt vmcnt(0)" ::: "memory");
.LBB9_739:
	s_andn2_saveexec_b64 s[2:3], s[8:9]
	s_cbranch_execz .LBB9_759
	s_mov_b64 s[2:3], exec
	v_mov_b32_e32 v1, 0x24008
	ds_read_b32 v1, v1
	s_waitcnt lgkmcnt(0)
	v_readfirstlane_b32 s98, v1
	s_nop 3
	s_cmp_eq_u32 s98, 1
	s_nop 0
	buffer_wbl2 sc1

; __device__ __forceinline__ unsigned xb_ld(unsigned* p)              { return __hip_atomic_load(p, __ATOMIC_RELAXED, __HIP_MEMORY_SCOPE_AGENT); }
; __device__ __forceinline__ unsigned xb_add(unsigned* p, unsigned v) { return __hip_atomic_fetch_add(p, v, __ATOMIC_RELAXED, __HIP_MEMORY_SCOPE_AGENT); }
; #define XB_SPIN(cond, bar) do { unsigned _sp = 0; while (cond) { __builtin_amdgcn_s_sleep(1); \
;     if ((++_sp & 255u) == 0u) { if (xb_ld(&(bar)[XB_TMO])) break; if (_sp > XB_SPIN_CAP) { atomicAdd(&(bar)[XB_TMO], 1u); break; } } } } while (0)
; #define SEAM(k) do { if (IN(k) && IN((k) + 1)) GRID_SYNC(); } while (0)
; __device__ __forceinline__ void xcd_barrier(const XcdBarrier& b) {
;     asm volatile("s_waitcnt vmcnt(0)" ::: "memory");
;     __syncthreads();
;     if (threadIdx.x == 0) {
;         unsigned* bar = b.bar;
;         __builtin_amdgcn_s_waitcnt(0);
;         unsigned nloc = b.st[0], nx = b.st[1];
;         if (nloc == 0u) { xcd_barrier_complete(bar, b.x, nloc, nx); b.st[0] = nloc; b.st[1] = nx; }
;         const unsigned old = xb_add(&bar[XB_XSUB(b.x)], 1u);
;         const unsigned gen = old / nloc;
;         if (old + 1u == (gen + 1u) * nloc) {
;             __builtin_amdgcn_fence(__ATOMIC_RELEASE, "agent");
;             asm volatile("s_waitcnt vmcnt(0)" ::: "memory");
;             const unsigned og = xb_add(&bar[XB_TOP], 1u);
;             const unsigned tg = og / nx;
;             if (og + 1u == (tg + 1u) * nx) xb_add(&bar[XB_TOPGEN], 1u);
;             else XB_SPIN(xb_ld(&bar[XB_TOPGEN]) == tg, bar);
;             __builtin_amdgcn_fence(__ATOMIC_ACQUIRE, "agent");
;             xb_add(&bar[XB_XGEN(b.x)], 1u);
;             asm volatile("s_waitcnt vmcnt(0)" ::: "memory");
;         } else {
;             XB_SPIN(xb_ld(&bar[XB_XGEN(b.x)]) == gen, bar);
;             __builtin_amdgcn_fence(__ATOMIC_ACQUIRE, "agent");
;             asm volatile("s_waitcnt vmcnt(0)" ::: "memory");
;         }
;     }
;     __syncthreads();
; }
; __global__ void __launch_bounds__(NTHR, 2) mk_fwd(MkArgs a) {
;     ...
;     SEAM(6);
.LBB9_777:
	s_cmp_gt_i32 s93, 7
	s_cselect_b64 s[0:1], -1, 0
	s_and_b64 s[2:3], s[4:5], s[0:1]
	s_andn2_b64 vcc, exec, s[2:3]
	s_cbranch_vccnz .LBB9_831
	s_waitcnt vmcnt(0)
	s_waitcnt vmcnt(0) lgkmcnt(0)
	s_barrier
	s_and_saveexec_b64 s[4:5], s[80:81]
	s_cbranch_execz .LBB9_830
	v_mov_b32_e32 v0, 0x24008
	ds_read_b32 v0, v0
	s_waitcnt lgkmcnt(0)
	v_readfirstlane_b32 s98, v0
	s_nop 3
	s_cmp_eq_u32 s98, 1
	s_cbranch_scc0 .Lgb6_orig
	s_and_b32 s98, s97, 63
	s_lshl_b32 s98, s98, 2
	s_add_i32 s98, s98, 0x3e00
	v_mov_b32_e32 v0, s98
	v_mov_b32_e32 v1, 1
	global_atomic_add v0, v1, s[90:91]
